# GLA prompt recurrence: chunk loop unrolled x2, operands staged two chunks ahead in a second register set, counted vmcnt 11..8
# speedup vs baseline: 1.0116x; 1.0013x over previous
; __device__ __forceinline__ void gla_prompt_unit(const Args& a, unsigned char* lds, int unit, int tid) {
;     ...
;     for (int i = tid; i < 33792 / 16; i += 512) ((u32x4*)ST)[i] = (u32x4){0u, 0u, 0u, 0u};
;     f32x4 sacc[2][4];
; #pragma unroll
;     for (int i = 0; i < 2; ++i)
; #pragma unroll
;         for (int j = 0; j < 4; ++j) sacc[i][j] = (f32x4){0.f, 0.f, 0.f, 0.f};
;     const size_t rowbase = (size_t)b * 2048;
;     u32x4 rq[2], rkd[2], rv = (u32x4){0u, 0u, 0u, 0u}, ram = (u32x4){0u, 0u, 0u, 0u}, rdec = (u32x4){0u, 0u, 0u, 0u};
;     ...
;     GLA_LOAD(0);
.LBB0_497:
	s_or_b64 exec, exec, s[26:27]
	s_lshl_b32 s50, s33, 7
	s_mul_i32 s48, s36, 0x2f00000
	s_and_b32 s50, s50, 0xc00
	s_and_b32 s0, s44, 7
	s_mul_hi_i32 s49, s36, 0x2f00000
	s_or_b32 s48, s48, s50
	v_or_b32_e32 v108, s34, v70
	s_lshl_b32 s34, s33, 4
	s_lshl_b64 s[26:27], s[30:31], 19
	s_lshl_b32 s0, s0, 4
	v_lshl_add_u64 v[2:3], s[48:49], 0, v[86:87]
	s_lshl_b64 s[48:49], s[30:31], 17
	s_lshl_b64 s[30:31], s[30:31], 16
	s_and_b32 s34, s34, 0x180
	v_lshl_add_u64 v[106:107], v[90:91], 0, s[30:31]
	s_lshl_b64 s[30:31], s[36:37], 20
	s_or_b32 s0, s0, s34
	v_lshlrev_b64 v[10:11], 1, v[102:103]
	s_or_b32 s30, s30, s0
	s_mul_i32 s0, s36, 0xc00000
	v_mul_lo_u32 v1, v9, s3
	v_lshl_add_u64 v[2:3], v[2:3], 0, v[10:11]
	v_lshlrev_b32_e32 v8, 1, v8
	v_mov_b32_e32 v9, v0
	v_lshl_add_u64 v[110:111], s[30:31], 0, v[92:93]
	s_mul_hi_i32 s31, s36, 0xc00000
	s_or_b32 s30, s0, s50
	v_lshl_add_u64 v[2:3], v[2:3], 0, v[8:9]
	v_lshl_add_u64 v[8:9], s[30:31], 0, v[94:95]
	v_lshl_add_u64 v[112:113], v[8:9], 0, v[10:11]
	v_mov_b32_e32 v8, 0
	v_lshl_add_u64 v[104:105], v[88:89], 0, s[48:49]
	v_mov_b32_e32 v109, s35
	s_mov_b32 s0, 63
	v_mov_b32_e32 v9, v8
	v_mov_b32_e32 v10, v8
	v_mov_b32_e32 v11, v8
	v_mov_b32_e32 v12, v8
	v_mov_b32_e32 v13, v8
	v_mov_b32_e32 v14, v8
	v_mov_b32_e32 v15, v8
	v_mov_b32_e32 v16, v8
	v_mov_b32_e32 v17, v8
	v_mov_b32_e32 v18, v8
	v_mov_b32_e32 v19, v8
	v_mov_b32_e32 v20, v8
	v_mov_b32_e32 v21, v8
	v_mov_b32_e32 v22, v8
	v_mov_b32_e32 v23, v8
	v_mov_b32_e32 v24, v8
	v_mov_b32_e32 v25, v8
	v_mov_b32_e32 v26, v8
	v_mov_b32_e32 v27, v8
	v_mov_b32_e32 v28, v8
	v_mov_b32_e32 v29, v8
	v_mov_b32_e32 v30, v8
	v_mov_b32_e32 v31, v8
	v_mov_b32_e32 v32, v8
	v_mov_b32_e32 v33, v8
	v_mov_b32_e32 v34, v8
	v_mov_b32_e32 v35, v8
	v_mov_b32_e32 v36, v8
	v_mov_b32_e32 v37, v8
	v_mov_b32_e32 v38, v8
	v_mov_b32_e32 v39, v8
	v_lshl_add_u64 v[206:207], s[86:87], 0, v[108:109]
	v_add_co_u32_e32 v198, vcc, 0x2ad04000, v206
	s_nop 1
	v_addc_co_u32_e32 v199, vcc, 0, v207, vcc
	v_add_co_u32_e32 v202, vcc, 0x2cd04000, v206
	s_nop 1
	v_addc_co_u32_e32 v203, vcc, 0, v207, vcc
	v_add_co_u32_e32 v208, vcc, 0x2ad06000, v206
	global_load_dwordx4 v[198:201], v[198:199], off
	s_nop 0
	global_load_dwordx4 v[202:205], v[202:203], off
	v_addc_co_u32_e32 v209, vcc, 0, v207, vcc
	v_add_co_u32_e32 v210, vcc, 0x2cd06000, v206
	s_nop 1
	v_addc_co_u32_e32 v211, vcc, 0, v207, vcc
	global_load_dwordx4 v[206:209], v[208:209], off
	s_nop 0
	global_load_dwordx4 v[210:213], v[210:211], off
	s_and_saveexec_b64 s[30:31], s[4:5]
	s_cbranch_execz .Lgr_p1
	v_lshl_add_u64 v[194:195], s[86:87], 0, v[104:105]
	global_load_dwordx4 v[194:197], v[194:195], off
.Lgr_p1:
	s_or_b64 exec, exec, s[30:31]
	s_and_saveexec_b64 s[30:31], s[6:7]
	s_cbranch_execz .Lgr_p2
	v_lshl_add_u64 v[190:191], s[86:87], 0, v[106:107]
	global_load_dwordx4 v[190:193], v[190:191], off
.Lgr_p2:
	s_or_b64 exec, exec, s[30:31]
	s_and_saveexec_b64 s[30:31], s[8:9]
	s_cbranch_execz .Lgr_p3
	v_lshl_add_u64 v[214:215], s[86:87], 0, v[2:3]
	global_load_dwordx4 v[214:217], v[214:215], off
.Lgr_p3:
	s_or_b64 exec, exec, s[30:31]
	v_lshl_add_u64 v[2:3], v[2:3], 0, s[14:15]
	v_lshl_add_u64 v[104:105], v[104:105], 0, s[16:17]
	v_lshl_add_u64 v[106:107], v[106:107], 0, s[18:19]
	v_lshl_add_u64 v[108:109], v[108:109], 0, s[20:21]
	s_waitcnt vmcnt(0)
	s_branch .LBB0_499

; __device__ __forceinline__ void gla_prompt_unit(const Args& a, unsigned char* lds, int unit, int tid) {
;     ...
; #pragma unroll
;         for (int i = 0; i < 2; ++i) { const int ch = tid + i * 512; *(u32x4*)(QI + (ch >> 5) * 528 + (ch & 31) * 16) = rq[i]; *(u32x4*)(KDT + (ch >> 2) * 80 + (ch & 3) * 16) = rkd[i]; }
;         if (tid < 128) *(u32x4*)(AM + (tid >> 2) * 80 + (tid & 3) * 16) = ram;
;         if (tid >= 128 && tid < 192) *(u32x4*)(DEC + (tid - 128) * 4) = rdec;
.Lgr_o499:
	s_waitcnt vmcnt(11)
	ds_write_b128 v126, v[198:201]
	s_waitcnt vmcnt(10)
	ds_write_b128 v127, v[202:205] offset:33792
	s_waitcnt vmcnt(9)
	ds_write_b128 v128, v[206:209]
	s_waitcnt vmcnt(8)
	ds_write_b128 v129, v[210:213] offset:33792
	s_and_saveexec_b64 s[30:31], s[4:5]
	s_cbranch_execnz .Lgr_o509
	s_or_b64 exec, exec, s[30:31]
	s_and_saveexec_b64 s[30:31], s[6:7]
	s_cbranch_execnz .Lgr_o510

; __device__ __forceinline__ void gla_prompt_unit(const Args& a, unsigned char* lds, int unit, int tid) {
;     ...
;         if (tid >= 256) { const int l = tid & 31, c8 = (tid - 256) >> 5; bf16_t* vt = (bf16_t*)VT + (c8 * 8) * 40 + l;
;             vt[0 * 40] = (bf16_t)(rv.x & 0xffffu); vt[1 * 40] = (bf16_t)(rv.x >> 16); vt[2 * 40] = (bf16_t)(rv.y & 0xffffu); vt[3 * 40] = (bf16_t)(rv.y >> 16);
;             vt[4 * 40] = (bf16_t)(rv.z & 0xffffu); vt[5 * 40] = (bf16_t)(rv.z >> 16); vt[6 * 40] = (bf16_t)(rv.w & 0xffffu); vt[7 * 40] = (bf16_t)(rv.w >> 16); }
;         if (n + 1 < 64) GLA_LOAD(n + 1);
.Lgr_o502:
	v_add_u32_e32 v198, v81, v1
	ds_write_b16 v198, v214
	ds_write_b16_d16_hi v198, v214 offset:80
	ds_write_b16 v198, v215 offset:160
	ds_write_b16_d16_hi v198, v215 offset:240
	ds_write_b16 v198, v216 offset:320
	ds_write_b16_d16_hi v198, v216 offset:400
	ds_write_b16 v198, v217 offset:480
	ds_write_b16_d16_hi v198, v217 offset:560
.Lgr_o503:
	s_or_b64 exec, exec, s[30:31]
	v_lshl_add_u64 v[206:207], s[86:87], 0, v[108:109]
	v_add_co_u32_e32 v198, vcc, 0x2ad04000, v206
	s_nop 1
	v_addc_co_u32_e32 v199, vcc, 0, v207, vcc
	v_add_co_u32_e32 v202, vcc, 0x2cd04000, v206
	s_nop 1
	v_addc_co_u32_e32 v203, vcc, 0, v207, vcc
	v_add_co_u32_e32 v208, vcc, 0x2ad06000, v206
	global_load_dwordx4 v[198:201], v[198:199], off
	s_nop 0
	global_load_dwordx4 v[202:205], v[202:203], off
	v_addc_co_u32_e32 v209, vcc, 0, v207, vcc
	v_add_co_u32_e32 v210, vcc, 0x2cd06000, v206
	s_nop 1
	v_addc_co_u32_e32 v211, vcc, 0, v207, vcc
	global_load_dwordx4 v[206:209], v[208:209], off
	s_nop 0
	global_load_dwordx4 v[210:213], v[210:211], off
	s_and_saveexec_b64 s[30:31], s[4:5]
	s_cbranch_execnz .Lgr_o511
	s_or_b64 exec, exec, s[30:31]
	s_and_saveexec_b64 s[30:31], s[6:7]
	s_cbranch_execnz .Lgr_o512

.Lgr_o506:
	v_lshl_add_u64 v[214:215], s[86:87], 0, v[2:3]
	global_load_dwordx4 v[214:217], v[214:215], off

; __device__ __forceinline__ unsigned cvt_pk_bf16(float lo, float hi) { unsigned r; asm volatile("v_cvt_pk_bf16_f32 %0, %1, %2" : "=v"(r) : "v"(lo), "v"(hi)); return r; }
; #define MFMA_SETTLE8(a, b, c, d, e, f, g, h) asm volatile("s_nop 15\n\ts_nop 15" : "+v"(a), "+v"(b), "+v"(c), "+v"(d), "+v"(e), "+v"(f), "+v"(g), "+v"(h))
; #define LBAR() asm volatile("s_waitcnt lgkmcnt(0)\n\ts_barrier" ::: "memory")
; __device__ __forceinline__ void gla_prompt_unit(const Args& a, unsigned char* lds, int unit, int tid) {
;     ...
;         if (tid < 128) *(u32x4*)(AM + (tid >> 2) * 80 + (tid & 3) * 16) = ram;
;         if (tid >= 128 && tid < 192) *(u32x4*)(DEC + (tid - 128) * 4) = rdec;
;     ...
; #pragma unroll
;         for (int k2 = 0; k2 < 2; ++k2) { const int kt = wave * 2 + k2; const f32x4 dec4 = *(const f32x4*)(DEC + kt * 16 + q4 * 4); const bf16x8 af = *(const bf16x8*)(KDT + (kt * 16 + r16) * 80 + q4 * 16);
; #pragma unroll
;             for (int v2 = 0; v2 < 4; ++v2) { const bf16x8 bfg = *(const bf16x8*)(VT + (v2 * 16 + r16) * 80 + q4 * 16);
;                 sacc[k2][v2] = __builtin_amdgcn_mfma_f32_16x16x32_bf16(af, bfg, sacc[k2][v2] * dec4, 0, 0, 0); } }
;         MFMA_SETTLE8(sacc[0][0], sacc[0][1], sacc[0][2], sacc[0][3], sacc[1][0], sacc[1][1], sacc[1][2], sacc[1][3]);
; #pragma unroll
;         for (int k2 = 0; k2 < 2; ++k2) { const int kt = wave * 2 + k2;
; #pragma unroll
;             for (int v2 = 0; v2 < 4; ++v2)
;                 *(u32x2*)(ST + (v2 * 16 + r16) * 528 + (kt * 16 + q4 * 4) * 2) = (u32x2){cvt_pk_bf16(sacc[k2][v2][0], sacc[k2][v2][1]), cvt_pk_bf16(sacc[k2][v2][2], sacc[k2][v2][3])}; }
;         LBAR();
.Lgr_o509:
	v_add_u32_e32 v198, v77, v75
	ds_write_b128 v198, v[194:197]
	s_or_b64 exec, exec, s[30:31]
	s_and_saveexec_b64 s[30:31], s[6:7]
	s_cbranch_execz .Lgr_o501
.Lgr_o510:
	ds_write_b128 v79, v[190:193]
	s_or_b64 exec, exec, s[30:31]
	s_and_saveexec_b64 s[30:31], s[8:9]
	s_cbranch_execnz .Lgr_o502
	s_branch .Lgr_o503
.Lgr_o511:
	v_lshl_add_u64 v[194:195], s[86:87], 0, v[104:105]
	global_load_dwordx4 v[194:197], v[194:195], off
	s_or_b64 exec, exec, s[30:31]
	s_and_saveexec_b64 s[30:31], s[6:7]
	s_cbranch_execz .Lgr_o505
.Lgr_o512:
	v_lshl_add_u64 v[190:191], s[86:87], 0, v[106:107]
	global_load_dwordx4 v[190:193], v[190:191], off
	s_or_b64 exec, exec, s[30:31]
	s_and_saveexec_b64 s[30:31], s[8:9]
	s_cbranch_execnz .Lgr_o506
	s_branch .Lgr_o507
.Lgr_o498:
	s_or_b64 exec, exec, s[30:31]
	s_waitcnt lgkmcnt(0)
	s_barrier
	ds_read_b128 v[142:145], v135 offset:33792
	ds_read_b128 v[150:153], v114
	ds_read_b128 v[154:157], v136
	ds_read_b128 v[158:161], v136 offset:1280
	ds_read_b128 v[162:165], v114 offset:64
	ds_read_b128 v[166:169], v136 offset:2560
	ds_read_b128 v[170:173], v136 offset:3840
	ds_read_b128 v[174:177], v137 offset:33792
	s_waitcnt lgkmcnt(6)
	v_pk_mul_f32 v[38:39], v[38:39], v[152:153]
	v_pk_mul_f32 v[36:37], v[36:37], v[150:151]
	v_pk_mul_f32 v[34:35], v[34:35], v[152:153]
	v_pk_mul_f32 v[32:33], v[32:33], v[150:151]
	v_pk_mul_f32 v[30:31], v[30:31], v[152:153]
	v_pk_mul_f32 v[28:29], v[28:29], v[150:151]
	v_pk_mul_f32 v[26:27], v[26:27], v[152:153]
	v_pk_mul_f32 v[24:25], v[24:25], v[150:151]
	s_waitcnt lgkmcnt(3)
	v_pk_mul_f32 v[22:23], v[22:23], v[164:165]
	v_pk_mul_f32 v[20:21], v[20:21], v[162:163]
	v_pk_mul_f32 v[18:19], v[18:19], v[164:165]
	v_pk_mul_f32 v[16:17], v[16:17], v[162:163]
	v_pk_mul_f32 v[14:15], v[14:15], v[164:165]
	v_pk_mul_f32 v[12:13], v[12:13], v[162:163]
	v_pk_mul_f32 v[10:11], v[10:11], v[164:165]
	v_pk_mul_f32 v[8:9], v[8:9], v[162:163]
	v_mfma_f32_16x16x32_bf16 v[36:39], v[142:145], v[154:157], v[36:39]
	s_add_i32 s0, s0, -1
	v_lshl_add_u64 v[2:3], v[2:3], 0, s[14:15]
	v_lshl_add_u64 v[104:105], v[104:105], 0, s[16:17]
	v_mfma_f32_16x16x32_bf16 v[32:35], v[142:145], v[158:161], v[32:35]
	v_lshl_add_u64 v[106:107], v[106:107], 0, s[18:19]
	v_lshl_add_u64 v[108:109], v[108:109], 0, s[20:21]
	v_lshl_add_u64 v[110:111], v[110:111], 0, s[20:21]
	s_waitcnt lgkmcnt(2)
	v_mfma_f32_16x16x32_bf16 v[28:31], v[142:145], v[166:169], v[28:31]
	s_cmp_eq_u32 s0, 0
	v_lshl_add_u64 v[112:113], v[112:113], 0, s[22:23]
	s_waitcnt lgkmcnt(1)
	v_mfma_f32_16x16x32_bf16 v[24:27], v[142:145], v[170:173], v[24:27]
	s_waitcnt lgkmcnt(0)
	v_mfma_f32_16x16x32_bf16 v[20:23], v[174:177], v[154:157], v[20:23]
	v_mfma_f32_16x16x32_bf16 v[16:19], v[174:177], v[158:161], v[16:19]
	v_mfma_f32_16x16x32_bf16 v[12:15], v[174:177], v[166:169], v[12:15]
	v_mfma_f32_16x16x32_bf16 v[8:11], v[174:177], v[170:173], v[8:11]
	s_nop 15
	s_nop 15
	s_nop 0
	v_cvt_pk_bf16_f32 v142, v36, v37
	v_cvt_pk_bf16_f32 v143, v38, v39
	ds_write_b64 v138, v[142:143] offset:54272
	v_cvt_pk_bf16_f32 v142, v32, v33
	v_cvt_pk_bf16_f32 v143, v34, v35
	ds_write_b64 v138, v[142:143] offset:62720
	v_cvt_pk_bf16_f32 v142, v28, v29
	v_cvt_pk_bf16_f32 v143, v30, v31
	ds_write_b64 v139, v[142:143] offset:54272
	v_cvt_pk_bf16_f32 v142, v24, v25
	v_cvt_pk_bf16_f32 v143, v26, v27
	ds_write_b64 v139, v[142:143] offset:62720
	v_cvt_pk_bf16_f32 v142, v20, v21
	v_cvt_pk_bf16_f32 v143, v22, v23
	ds_write_b64 v138, v[142:143] offset:54304
	v_cvt_pk_bf16_f32 v142, v16, v17
	v_cvt_pk_bf16_f32 v143, v18, v19
	ds_write_b64 v138, v[142:143] offset:62752
	v_cvt_pk_bf16_f32 v142, v12, v13
	v_cvt_pk_bf16_f32 v143, v14, v15
	ds_write_b64 v139, v[142:143] offset:54304
	v_cvt_pk_bf16_f32 v142, v8, v9
	v_cvt_pk_bf16_f32 v143, v10, v11
	ds_write_b64 v139, v[142:143] offset:62752
	s_waitcnt lgkmcnt(0)
	s_barrier
	s_cbranch_scc1 .LBB0_513
	s_branch .LBB0_499
.LBB0_499:
	s_waitcnt vmcnt(11)
	ds_write_b128 v126, v[48:51]
	s_waitcnt vmcnt(10)
	ds_write_b128 v127, v[52:55] offset:33792
	s_waitcnt vmcnt(9)
	ds_write_b128 v128, v[56:59]
	s_waitcnt vmcnt(8)
	ds_write_b128 v129, v[60:63] offset:33792
	s_and_saveexec_b64 s[30:31], s[4:5]
	s_cbranch_execnz .LBB0_509
	s_or_b64 exec, exec, s[30:31]
	s_and_saveexec_b64 s[30:31], s[6:7]
	s_cbranch_execnz .LBB0_510

; __device__ __forceinline__ void gla_prompt_unit(const Args& a, unsigned char* lds, int unit, int tid) {
;     ...
;         if (n + 1 < 64) GLA_LOAD(n + 1);
.LBB0_503:
	s_or_b64 exec, exec, s[30:31]
	s_cmp_eq_u32 s0, 1
	s_cbranch_scc1 .LBB0_507
	v_lshl_add_u64 v[56:57], s[86:87], 0, v[108:109]
	v_add_co_u32_e32 v48, vcc, 0x2ad04000, v56
	s_nop 1
	v_addc_co_u32_e32 v49, vcc, 0, v57, vcc
	v_add_co_u32_e32 v52, vcc, 0x2cd04000, v56
	s_nop 1
	v_addc_co_u32_e32 v53, vcc, 0, v57, vcc
	v_add_co_u32_e32 v58, vcc, 0x2ad06000, v56
	global_load_dwordx4 v[48:51], v[48:49], off
	s_nop 0
	global_load_dwordx4 v[52:55], v[52:53], off
	v_addc_co_u32_e32 v59, vcc, 0, v57, vcc
	v_add_co_u32_e32 v60, vcc, 0x2cd06000, v56
	s_nop 1
	v_addc_co_u32_e32 v61, vcc, 0, v57, vcc
	global_load_dwordx4 v[56:59], v[58:59], off
	s_nop 0
	global_load_dwordx4 v[60:63], v[60:61], off
	s_and_saveexec_b64 s[30:31], s[4:5]
	s_cbranch_execnz .LBB0_511
	s_or_b64 exec, exec, s[30:31]
	s_and_saveexec_b64 s[30:31], s[6:7]
	s_cbranch_execnz .LBB0_512

; __device__ __forceinline__ void gla_prompt_unit(const Args& a, unsigned char* lds, int unit, int tid) {
;     ...
; #pragma unroll
;         for (int i = 0; i < 2; ++i) { const int ch = tid + i * 512; *(u32x4*)(QI + (ch >> 5) * 528 + (ch & 31) * 16) = rq[i]; *(u32x4*)(KDT + (ch >> 2) * 80 + (ch & 3) * 16) = rkd[i]; }
;         if (tid < 128) *(u32x4*)(AM + (tid >> 2) * 80 + (tid & 3) * 16) = ram;
;         if (tid >= 128 && tid < 192) *(u32x4*)(DEC + (tid - 128) * 4) = rdec;
.LBB0_513:
	s_waitcnt vmcnt(4)
	ds_write_b128 v126, v[198:201]
	s_waitcnt vmcnt(3)
	ds_write_b128 v127, v[202:205] offset:33792
	s_waitcnt vmcnt(2)
	ds_write_b128 v128, v[206:209]
	s_waitcnt vmcnt(1)
	ds_write_b128 v129, v[210:213] offset:33792
	s_and_saveexec_b64 s[30:31], s[4:5]
	s_cbranch_execnz .LBB0_519
	s_or_b64 exec, exec, s[30:31]
	s_and_saveexec_b64 s[30:31], s[6:7]
	s_cbranch_execnz .LBB0_520

; __device__ __forceinline__ void gla_prompt_unit(const Args& a, unsigned char* lds, int unit, int tid) {
;     ...
;         if (tid >= 256) { const int l = tid & 31, c8 = (tid - 256) >> 5; bf16_t* vt = (bf16_t*)VT + (c8 * 8) * 40 + l;
;             vt[0 * 40] = (bf16_t)(rv.x & 0xffffu); vt[1 * 40] = (bf16_t)(rv.x >> 16); vt[2 * 40] = (bf16_t)(rv.y & 0xffffu); vt[3 * 40] = (bf16_t)(rv.y >> 16);
;             vt[4 * 40] = (bf16_t)(rv.z & 0xffffu); vt[5 * 40] = (bf16_t)(rv.z >> 16); vt[6 * 40] = (bf16_t)(rv.w & 0xffffu); vt[7 * 40] = (bf16_t)(rv.w >> 16); }
.LBB0_516:
	v_add_u32_e32 v1, v81, v1
	ds_write_b16 v1, v214
	ds_write_b16_d16_hi v1, v214 offset:80
	ds_write_b16 v1, v215 offset:160
	ds_write_b16_d16_hi v1, v215 offset:240
	ds_write_b16 v1, v216 offset:320
	ds_write_b16_d16_hi v1, v216 offset:400
	ds_write_b16 v1, v217 offset:480
	ds_write_b16_d16_hi v1, v217 offset:560

; __device__ __forceinline__ void gla_prompt_unit(const Args& a, unsigned char* lds, int unit, int tid) {
;     ...
;         if (tid < 128) *(u32x4*)(AM + (tid >> 2) * 80 + (tid & 3) * 16) = ram;
.LBB0_519:
	v_add_u32_e32 v2, v77, v75
	ds_write_b128 v2, v[194:197]
	s_or_b64 exec, exec, s[30:31]
	s_and_saveexec_b64 s[30:31], s[6:7]
	s_cbranch_execz .LBB0_515
